# attention: softmax exponent via one fma per element (s*log2e - m*log2e) in the 64-key rounds; SWA local-tile PV fragments read straight into MFMA operand order (24 v_mov per tile removed)
# speedup vs baseline: 1.0037x; 1.0037x over previous
; #define LAS __attribute__((address_space(3)))
; DI unsigned pk2(float lo, float hi) { const f32x2 v = {lo, hi}; const hbf16x2 b = __builtin_convertvector(v, hbf16x2); return __builtin_bit_cast(unsigned, b); }
; #define MFMA16(a, b, c) __builtin_amdgcn_mfma_f32_16x16x32_bf16((a), (b), (c), 0, 0, 0)
; template <bool SWA>
; DI void attn_phase(const Ctx& a, LAS unsigned char* lds) {
;     ...
;                 const float m_new = fmaxf(m_run, cmax);
;                 const float alpha = __builtin_amdgcn_exp2f((m_run - m_new) * LOG2E);
;                 float p[16], psum = 0.f;
; #pragma unroll
;                 for (int e = 0; e < 16; ++e) { p[e] = ok[e] ? __builtin_amdgcn_exp2f((sv[e] - m_new) * LOG2E) : 0.f; psum += p[e]; }
;                 l_run = l_run * alpha + psum; m_run = m_new;
;                 u32x4 pw0, pw1; pw0.x = pk2(p[0], p[1]); pw0.y = pk2(p[2], p[3]); pw0.z = pk2(p[4], p[5]); pw0.w = pk2(p[6], p[7]);
;                 pw1.x = pk2(p[8], p[9]); pw1.y = pk2(p[10], p[11]); pw1.z = pk2(p[12], p[13]); pw1.w = pk2(p[14], p[15]);
;                 const bf16x8 pf0 = __builtin_bit_cast(bf16x8, pw0), pf1 = __builtin_bit_cast(bf16x8, pw1);
;                 if (__builtin_amdgcn_ballot_w64(alpha != 1.f) != 0ull) {
; #pragma unroll
;                     for (int dt = 0; dt < 4; ++dt) o[dt] = o[dt] * alpha;
;                 }
;                 const int kc = (fq >> 1), kb8 = (fq & 1) * 8;
; #pragma unroll
;                 for (int dt = 0; dt < 4; ++dt) {
;                     const int d = 16 * dt + fr, sw = (d >> 1) & 7; const int vb = AT_V + buf * 8192 + d * 128 + kb8;
;                     const s16x4 v0 = *(const LAS s16x4*)(lds + vb + ((kc ^ sw) << 4)), v1 = *(const LAS s16x4*)(lds + vb + (((kc + 2) ^ sw) << 4));
;                     const s16x4 v2 = *(const LAS s16x4*)(lds + vb + (((kc + 4) ^ sw) << 4)), v3 = *(const LAS s16x4*)(lds + vb + (((kc + 6) ^ sw) << 4));
;                     o[dt] = MFMA16(__builtin_shufflevector(v0, v1, 0, 1, 2, 3, 4, 5, 6, 7), pf0, o[dt]);
;                     o[dt] = MFMA16(__builtin_shufflevector(v2, v3, 0, 1, 2, 3, 4, 5, 6, 7), pf1, o[dt]);
;                 }
.LBB0_87:
	ds_read2st64_b64 v[90:93], v77 offset0:64 offset1:68
	s_mov_b32 s98, 0x3fb8aa3b
	v_mul_f32_e32 v190, 0xbfb8aa3b, v85
	v_fma_f32 v24, v24, s98, v190
	v_fma_f32 v25, v25, s98, v190
	v_fma_f32 v26, v26, s98, v190
	v_fma_f32 v27, v27, s98, v190
	v_fma_f32 v28, v28, s98, v190
	v_fma_f32 v29, v29, s98, v190
	v_fma_f32 v30, v30, s98, v190
	v_fma_f32 v31, v31, s98, v190
	v_exp_f32_e32 v24, v24
	v_exp_f32_e32 v25, v25
	v_exp_f32_e32 v26, v26
	v_exp_f32_e32 v27, v27
	v_exp_f32_e32 v28, v28
	v_exp_f32_e32 v29, v29
	v_exp_f32_e32 v30, v30
	v_exp_f32_e32 v31, v31
	s_waitcnt lgkmcnt(0)
	v_mov_b32_e32 v96, v90
	v_mov_b32_e32 v97, v91
	ds_read2st64_b64 v[98:101], v78 offset0:64 offset1:68
	ds_read2st64_b64 v[102:105], v49 offset0:64 offset1:68
	ds_read2st64_b64 v[106:109], v76 offset0:64 offset1:68
	v_cvt_pk_bf16_f32 v86, v24, v25
	v_cvt_pk_bf16_f32 v87, v26, v27
	v_cvt_pk_bf16_f32 v88, v28, v29
	v_cvt_pk_bf16_f32 v89, v30, v31
	v_fma_f32 v32, v32, s98, v190
	v_fma_f32 v33, v33, s98, v190
	s_waitcnt lgkmcnt(0)
	v_mfma_f32_16x16x32_bf16 v[20:23], v[96:99], v[86:89], v[20:23]
	v_mov_b32_e32 v98, v92
	v_mov_b32_e32 v99, v93
	v_fma_f32 v34, v34, s98, v190
	v_fma_f32 v35, v35, s98, v190
	v_fma_f32 v36, v36, s98, v190
	v_fma_f32 v37, v37, s98, v190
	v_fma_f32 v38, v38, s98, v190
	v_fma_f32 v39, v39, s98, v190
	v_exp_f32_e32 v32, v32
	v_exp_f32_e32 v33, v33
	v_exp_f32_e32 v34, v34
	v_exp_f32_e32 v35, v35
	v_exp_f32_e32 v36, v36
	v_exp_f32_e32 v37, v37
	v_exp_f32_e32 v38, v38
	v_exp_f32_e32 v39, v39
	v_mov_b32_e32 v110, v102
	v_mov_b32_e32 v111, v103
	v_mov_b32_e32 v112, v106
	v_mov_b32_e32 v113, v107
	v_mfma_f32_16x16x32_bf16 v[8:11], v[98:101], v[86:89], v[8:11]
	v_mov_b32_e32 v106, v104
	v_mov_b32_e32 v107, v105
	ds_read2st64_b64 v[90:93], v77 offset0:72 offset1:76
	ds_read2st64_b64 v[98:101], v78 offset0:72 offset1:76
	v_cvt_pk_bf16_f32 v94, v32, v33
	v_cvt_pk_bf16_f32 v95, v34, v35
	v_cvt_pk_bf16_f32 v96, v36, v37
	v_cvt_pk_bf16_f32 v97, v38, v39
	s_waitcnt lgkmcnt(0)
	v_mov_b32_e32 v102, v90
	v_mov_b32_e32 v103, v91
	v_mfma_f32_16x16x32_bf16 v[20:23], v[110:113], v[94:97], v[20:23]
	v_mov_b32_e32 v104, v98
	v_mov_b32_e32 v105, v99
	v_mov_b32_e32 v98, v92
	v_mfma_f32_16x16x32_bf16 v[8:11], v[106:109], v[94:97], v[8:11]
	ds_read2st64_b64 v[106:109], v49 offset0:72 offset1:76
	ds_read2st64_b64 v[110:113], v76 offset0:72 offset1:76
	v_mov_b32_e32 v99, v93
	s_andn2_b64 vcc, exec, s[30:31]
	v_mfma_f32_16x16x32_bf16 v[4:7], v[102:105], v[86:89], v[4:7]
	s_waitcnt lgkmcnt(0)
	v_mov_b32_e32 v102, v106
	v_mov_b32_e32 v103, v107
	v_mov_b32_e32 v104, v110
	v_mov_b32_e32 v105, v111
	v_mov_b32_e32 v110, v108
	v_mov_b32_e32 v111, v109
	v_mfma_f32_16x16x32_bf16 v[0:3], v[98:101], v[86:89], v[0:3]
	s_mov_b64 s[30:31], -1
	v_mfma_f32_16x16x32_bf16 v[4:7], v[102:105], v[94:97], v[4:7]
	v_mfma_f32_16x16x32_bf16 v[0:3], v[110:113], v[94:97], v[0:3]
	s_cbranch_vccnz .LBB0_89
	s_waitcnt vmcnt(0)
	s_mov_b64 s[30:31], 0

; #define LAS __attribute__((address_space(3)))
; DI unsigned pk2(float lo, float hi) { const f32x2 v = {lo, hi}; const hbf16x2 b = __builtin_convertvector(v, hbf16x2); return __builtin_bit_cast(unsigned, b); }
; #define MFMA16(a, b, c) __builtin_amdgcn_mfma_f32_16x16x32_bf16((a), (b), (c), 0, 0, 0)
; template <bool SWA>
; DI void attn_phase(const Ctx& a, LAS unsigned char* lds) {
;     ...
;                 const float m_new = fmaxf(m_run, cmax);
;                 const float alpha = __builtin_amdgcn_exp2f((m_run - m_new) * LOG2E);
;                 float p[16], psum = 0.f;
; #pragma unroll
;                 for (int e = 0; e < 16; ++e) { p[e] = ok[e] ? __builtin_amdgcn_exp2f((sv[e] - m_new) * LOG2E) : 0.f; psum += p[e]; }
;                 l_run = l_run * alpha + psum; m_run = m_new;
;                 u32x4 pw0, pw1; pw0.x = pk2(p[0], p[1]); pw0.y = pk2(p[2], p[3]); pw0.z = pk2(p[4], p[5]); pw0.w = pk2(p[6], p[7]);
;                 pw1.x = pk2(p[8], p[9]); pw1.y = pk2(p[10], p[11]); pw1.z = pk2(p[12], p[13]); pw1.w = pk2(p[14], p[15]);
;                 const bf16x8 pf0 = __builtin_bit_cast(bf16x8, pw0), pf1 = __builtin_bit_cast(bf16x8, pw1);
;                 if (__builtin_amdgcn_ballot_w64(alpha != 1.f) != 0ull) {
; #pragma unroll
;                     for (int dt = 0; dt < 4; ++dt) o[dt] = o[dt] * alpha;
;                 }
;                 const int kc = (fq >> 1), kb8 = (fq & 1) * 8;
; #pragma unroll
;                 for (int dt = 0; dt < 4; ++dt) {
;                     const int d = 16 * dt + fr, sw = (d >> 1) & 7; const int vb = AT_V + buf * 8192 + d * 128 + kb8;
;                     const s16x4 v0 = *(const LAS s16x4*)(lds + vb + ((kc ^ sw) << 4)), v1 = *(const LAS s16x4*)(lds + vb + (((kc + 2) ^ sw) << 4));
;                     const s16x4 v2 = *(const LAS s16x4*)(lds + vb + (((kc + 4) ^ sw) << 4)), v3 = *(const LAS s16x4*)(lds + vb + (((kc + 6) ^ sw) << 4));
;                     o[dt] = MFMA16(__builtin_shufflevector(v0, v1, 0, 1, 2, 3, 4, 5, 6, 7), pf0, o[dt]);
;                     o[dt] = MFMA16(__builtin_shufflevector(v2, v3, 0, 1, 2, 3, 4, 5, 6, 7), pf1, o[dt]);
;                 }
.LBB0_96:
	ds_read2st64_b64 v[90:93], v77 offset0:80 offset1:84
	s_mov_b32 s98, 0x3fb8aa3b
	v_mul_f32_e32 v190, 0xbfb8aa3b, v82
	v_fma_f32 v24, v24, s98, v190
	v_fma_f32 v25, v25, s98, v190
	v_fma_f32 v26, v26, s98, v190
	v_fma_f32 v27, v27, s98, v190
	v_fma_f32 v28, v28, s98, v190
	v_fma_f32 v29, v29, s98, v190
	v_fma_f32 v30, v30, s98, v190
	v_fma_f32 v31, v31, s98, v190
	v_exp_f32_e32 v24, v24
	v_exp_f32_e32 v25, v25
	v_exp_f32_e32 v26, v26
	v_exp_f32_e32 v27, v27
	v_exp_f32_e32 v28, v28
	v_exp_f32_e32 v29, v29
	v_exp_f32_e32 v30, v30
	v_exp_f32_e32 v31, v31
	s_waitcnt lgkmcnt(0)
	v_mov_b32_e32 v96, v90
	v_mov_b32_e32 v97, v91
	ds_read2st64_b64 v[98:101], v78 offset0:80 offset1:84
	ds_read2st64_b64 v[102:105], v49 offset0:80 offset1:84
	ds_read2st64_b64 v[106:109], v76 offset0:80 offset1:84
	v_cvt_pk_bf16_f32 v86, v24, v25
	v_cvt_pk_bf16_f32 v87, v26, v27
	v_cvt_pk_bf16_f32 v88, v28, v29
	v_cvt_pk_bf16_f32 v89, v30, v31
	v_fma_f32 v32, v32, s98, v190
	v_fma_f32 v33, v33, s98, v190
	s_waitcnt lgkmcnt(0)
	v_mfma_f32_16x16x32_bf16 v[20:23], v[96:99], v[86:89], v[20:23]
	v_mov_b32_e32 v98, v92
	v_mov_b32_e32 v99, v93
	v_fma_f32 v34, v34, s98, v190
	v_fma_f32 v35, v35, s98, v190
	v_fma_f32 v36, v36, s98, v190
	v_fma_f32 v37, v37, s98, v190
	v_fma_f32 v38, v38, s98, v190
	v_fma_f32 v39, v39, s98, v190
	v_exp_f32_e32 v32, v32
	v_exp_f32_e32 v33, v33
	v_exp_f32_e32 v34, v34
	v_exp_f32_e32 v35, v35
	v_exp_f32_e32 v36, v36
	v_exp_f32_e32 v37, v37
	v_exp_f32_e32 v38, v38
	v_exp_f32_e32 v39, v39
	v_mov_b32_e32 v110, v102
	v_mov_b32_e32 v111, v103
	v_mov_b32_e32 v112, v106
	v_mov_b32_e32 v113, v107
	v_mfma_f32_16x16x32_bf16 v[8:11], v[98:101], v[86:89], v[8:11]
	v_mov_b32_e32 v106, v104
	v_mov_b32_e32 v107, v105
	ds_read2st64_b64 v[90:93], v77 offset0:88 offset1:92
	ds_read2st64_b64 v[98:101], v78 offset0:88 offset1:92
	v_cvt_pk_bf16_f32 v94, v32, v33
	v_cvt_pk_bf16_f32 v95, v34, v35
	v_cvt_pk_bf16_f32 v96, v36, v37
	v_cvt_pk_bf16_f32 v97, v38, v39
	s_waitcnt lgkmcnt(0)
	v_mov_b32_e32 v102, v90
	v_mov_b32_e32 v103, v91
	v_mfma_f32_16x16x32_bf16 v[20:23], v[110:113], v[94:97], v[20:23]
	v_mov_b32_e32 v104, v98
	v_mov_b32_e32 v105, v99
	v_mov_b32_e32 v98, v92
	v_mfma_f32_16x16x32_bf16 v[8:11], v[106:109], v[94:97], v[8:11]
	ds_read2st64_b64 v[106:109], v49 offset0:88 offset1:92
	ds_read2st64_b64 v[110:113], v76 offset0:88 offset1:92
	v_mov_b32_e32 v99, v93
	s_andn2_b64 vcc, exec, s[30:31]
	v_mfma_f32_16x16x32_bf16 v[4:7], v[102:105], v[86:89], v[4:7]
	s_waitcnt lgkmcnt(0)
	v_mov_b32_e32 v102, v106
	v_mov_b32_e32 v103, v107
	v_mov_b32_e32 v104, v110
	v_mov_b32_e32 v105, v111
	v_mov_b32_e32 v110, v108
	v_mov_b32_e32 v111, v109
	v_mfma_f32_16x16x32_bf16 v[0:3], v[98:101], v[86:89], v[0:3]
	s_mov_b64 s[30:31], -1
	v_mfma_f32_16x16x32_bf16 v[4:7], v[102:105], v[94:97], v[4:7]
	v_mfma_f32_16x16x32_bf16 v[0:3], v[110:113], v[94:97], v[0:3]
	s_cbranch_vccnz .LBB0_98
	s_waitcnt vmcnt(0)
	s_mov_b64 s[30:31], 0

; #define LAS __attribute__((address_space(3)))
; DI unsigned pk2(float lo, float hi) { const f32x2 v = {lo, hi}; const hbf16x2 b = __builtin_convertvector(v, hbf16x2); return __builtin_bit_cast(unsigned, b); }
; #define MFMA16(a, b, c) __builtin_amdgcn_mfma_f32_16x16x32_bf16((a), (b), (c), 0, 0, 0)
; template <bool SWA>
; DI void attn_phase(const Ctx& a, LAS unsigned char* lds) {
;     ...
;                 const float m_new = fmaxf(m_run, cmax);
;                 const float alpha = __builtin_amdgcn_exp2f((m_run - m_new) * LOG2E);
;                 float p[16], psum = 0.f;
; #pragma unroll
;                 for (int e = 0; e < 16; ++e) { p[e] = ok[e] ? __builtin_amdgcn_exp2f((sv[e] - m_new) * LOG2E) : 0.f; psum += p[e]; }
;                 l_run = l_run * alpha + psum; m_run = m_new;
;                 u32x4 pw0, pw1; pw0.x = pk2(p[0], p[1]); pw0.y = pk2(p[2], p[3]); pw0.z = pk2(p[4], p[5]); pw0.w = pk2(p[6], p[7]);
;                 pw1.x = pk2(p[8], p[9]); pw1.y = pk2(p[10], p[11]); pw1.z = pk2(p[12], p[13]); pw1.w = pk2(p[14], p[15]);
;                 const bf16x8 pf0 = __builtin_bit_cast(bf16x8, pw0), pf1 = __builtin_bit_cast(bf16x8, pw1);
;                 if (__builtin_amdgcn_ballot_w64(alpha != 1.f) != 0ull) {
; #pragma unroll
;                     for (int dt = 0; dt < 4; ++dt) o[dt] = o[dt] * alpha;
;                 }
;                 const int kc = (fq >> 1), kb8 = (fq & 1) * 8;
; #pragma unroll
;                 for (int dt = 0; dt < 4; ++dt) {
;                     const int d = 16 * dt + fr, sw = (d >> 1) & 7; const int vb = AT_V + buf * 8192 + d * 128 + kb8;
;                     const s16x4 v0 = *(const LAS s16x4*)(lds + vb + ((kc ^ sw) << 4)), v1 = *(const LAS s16x4*)(lds + vb + (((kc + 2) ^ sw) << 4));
;                     const s16x4 v2 = *(const LAS s16x4*)(lds + vb + (((kc + 4) ^ sw) << 4)), v3 = *(const LAS s16x4*)(lds + vb + (((kc + 6) ^ sw) << 4));
;                     o[dt] = MFMA16(__builtin_shufflevector(v0, v1, 0, 1, 2, 3, 4, 5, 6, 7), pf0, o[dt]);
;                     o[dt] = MFMA16(__builtin_shufflevector(v2, v3, 0, 1, 2, 3, 4, 5, 6, 7), pf1, o[dt]);
;                 }
.LBB0_105:
	ds_read2st64_b64 v[86:89], v77 offset0:48 offset1:52
	s_mov_b32 s98, 0x3fb8aa3b
	v_mul_f32_e32 v190, 0xbfb8aa3b, v79
	v_fma_f32 v24, v24, s98, v190
	v_fma_f32 v25, v25, s98, v190
	v_fma_f32 v26, v26, s98, v190
	v_fma_f32 v27, v27, s98, v190
	v_fma_f32 v28, v28, s98, v190
	v_fma_f32 v29, v29, s98, v190
	v_fma_f32 v30, v30, s98, v190
	v_fma_f32 v31, v31, s98, v190
	v_exp_f32_e32 v24, v24
	v_exp_f32_e32 v25, v25
	v_exp_f32_e32 v26, v26
	v_exp_f32_e32 v27, v27
	v_exp_f32_e32 v28, v28
	v_exp_f32_e32 v29, v29
	v_exp_f32_e32 v30, v30
	v_exp_f32_e32 v31, v31
	s_waitcnt lgkmcnt(0)
	v_mov_b32_e32 v92, v86
	v_mov_b32_e32 v93, v87
	ds_read2st64_b64 v[94:97], v78 offset0:48 offset1:52
	ds_read2st64_b64 v[98:101], v49 offset0:48 offset1:52
	ds_read2st64_b64 v[102:105], v76 offset0:48 offset1:52
	v_cvt_pk_bf16_f32 v82, v24, v25
	v_cvt_pk_bf16_f32 v83, v26, v27
	v_cvt_pk_bf16_f32 v84, v28, v29
	v_cvt_pk_bf16_f32 v85, v30, v31
	v_fma_f32 v32, v32, s98, v190
	v_fma_f32 v33, v33, s98, v190
	s_waitcnt lgkmcnt(0)
	v_mfma_f32_16x16x32_bf16 v[20:23], v[92:95], v[82:85], v[20:23]
	v_mov_b32_e32 v94, v88
	v_mov_b32_e32 v95, v89
	v_fma_f32 v34, v34, s98, v190
	v_fma_f32 v35, v35, s98, v190
	v_fma_f32 v36, v36, s98, v190
	v_fma_f32 v37, v37, s98, v190
	v_fma_f32 v38, v38, s98, v190
	v_fma_f32 v39, v39, s98, v190
	v_exp_f32_e32 v32, v32
	v_exp_f32_e32 v33, v33
	v_exp_f32_e32 v34, v34
	v_exp_f32_e32 v35, v35
	v_exp_f32_e32 v36, v36
	v_exp_f32_e32 v37, v37
	v_exp_f32_e32 v38, v38
	v_exp_f32_e32 v39, v39
	v_mov_b32_e32 v106, v98
	v_mov_b32_e32 v107, v99
	v_mov_b32_e32 v108, v102
	v_mov_b32_e32 v109, v103
	v_mfma_f32_16x16x32_bf16 v[8:11], v[94:97], v[82:85], v[8:11]
	v_mov_b32_e32 v102, v100
	v_mov_b32_e32 v103, v101
	ds_read2st64_b64 v[86:89], v77 offset0:56 offset1:60
	ds_read2st64_b64 v[94:97], v78 offset0:56 offset1:60
	v_cvt_pk_bf16_f32 v90, v32, v33
	v_cvt_pk_bf16_f32 v91, v34, v35
	v_cvt_pk_bf16_f32 v92, v36, v37
	v_cvt_pk_bf16_f32 v93, v38, v39
	s_waitcnt lgkmcnt(0)
	v_mov_b32_e32 v98, v86
	v_mov_b32_e32 v99, v87
	v_mfma_f32_16x16x32_bf16 v[20:23], v[106:109], v[90:93], v[20:23]
	v_mov_b32_e32 v100, v94
	v_mov_b32_e32 v101, v95
	v_mov_b32_e32 v94, v88
	v_mfma_f32_16x16x32_bf16 v[8:11], v[102:105], v[90:93], v[8:11]
	ds_read2st64_b64 v[102:105], v49 offset0:56 offset1:60
	ds_read2st64_b64 v[106:109], v76 offset0:56 offset1:60
	v_mov_b32_e32 v95, v89
	s_andn2_b64 vcc, exec, s[30:31]
	v_mfma_f32_16x16x32_bf16 v[4:7], v[98:101], v[82:85], v[4:7]
	s_waitcnt lgkmcnt(0)
	v_mov_b32_e32 v98, v102
	v_mov_b32_e32 v99, v103
	v_mov_b32_e32 v100, v106
	v_mov_b32_e32 v101, v107
	v_mov_b32_e32 v106, v104
	v_mov_b32_e32 v107, v105
	v_mfma_f32_16x16x32_bf16 v[0:3], v[94:97], v[82:85], v[0:3]
	s_mov_b64 s[30:31], -1
	v_mfma_f32_16x16x32_bf16 v[4:7], v[98:101], v[90:93], v[4:7]
	v_mfma_f32_16x16x32_bf16 v[0:3], v[106:109], v[90:93], v[0:3]
	s_cbranch_vccnz .LBB0_107
	s_waitcnt vmcnt(0)
	s_mov_b64 s[30:31], 0

; #define LAS __attribute__((address_space(3)))
; DI unsigned pk2(float lo, float hi) { const f32x2 v = {lo, hi}; const hbf16x2 b = __builtin_convertvector(v, hbf16x2); return __builtin_bit_cast(unsigned, b); }
; #define MFMA16(a, b, c) __builtin_amdgcn_mfma_f32_16x16x32_bf16((a), (b), (c), 0, 0, 0)
; template <bool SWA>
; DI void attn_phase(const Ctx& a, LAS unsigned char* lds) {
;     ...
;                 const float m_new = fmaxf(m_run, cmax);
;                 const float alpha = __builtin_amdgcn_exp2f((m_run - m_new) * LOG2E);
;                 float p[16], psum = 0.f;
; #pragma unroll
;                 for (int e = 0; e < 16; ++e) { p[e] = ok[e] ? __builtin_amdgcn_exp2f((sv[e] - m_new) * LOG2E) : 0.f; psum += p[e]; }
;                 l_run = l_run * alpha + psum; m_run = m_new;
;                 u32x4 pw0, pw1; pw0.x = pk2(p[0], p[1]); pw0.y = pk2(p[2], p[3]); pw0.z = pk2(p[4], p[5]); pw0.w = pk2(p[6], p[7]);
;                 pw1.x = pk2(p[8], p[9]); pw1.y = pk2(p[10], p[11]); pw1.z = pk2(p[12], p[13]); pw1.w = pk2(p[14], p[15]);
;                 const bf16x8 pf0 = __builtin_bit_cast(bf16x8, pw0), pf1 = __builtin_bit_cast(bf16x8, pw1);
;                 if (__builtin_amdgcn_ballot_w64(alpha != 1.f) != 0ull) {
; #pragma unroll
;                     for (int dt = 0; dt < 4; ++dt) o[dt] = o[dt] * alpha;
;                 }
;                 const int kc = (fq >> 1), kb8 = (fq & 1) * 8;
; #pragma unroll
;                 for (int dt = 0; dt < 4; ++dt) {
;                     const int d = 16 * dt + fr, sw = (d >> 1) & 7; const int vb = AT_V + buf * 8192 + d * 128 + kb8;
;                     const s16x4 v0 = *(const LAS s16x4*)(lds + vb + ((kc ^ sw) << 4)), v1 = *(const LAS s16x4*)(lds + vb + (((kc + 2) ^ sw) << 4));
;                     const s16x4 v2 = *(const LAS s16x4*)(lds + vb + (((kc + 4) ^ sw) << 4)), v3 = *(const LAS s16x4*)(lds + vb + (((kc + 6) ^ sw) << 4));
;                     o[dt] = MFMA16(__builtin_shufflevector(v0, v1, 0, 1, 2, 3, 4, 5, 6, 7), pf0, o[dt]);
;                     o[dt] = MFMA16(__builtin_shufflevector(v2, v3, 0, 1, 2, 3, 4, 5, 6, 7), pf1, o[dt]);
;                 }
.LBB0_115:
	v_add_u32_e32 v77, s79, v74
	v_add_u32_e32 v106, v77, v70
	v_add_u32_e32 v107, v77, v71
	ds_read_b64 v[116:117], v106 offset:24576
	ds_read_b64 v[118:119], v107 offset:24576
	ds_read_b64 v[120:121], v106 offset:26624
	ds_read_b64 v[122:123], v107 offset:26624
	s_mov_b32 s98, 0x3fb8aa3b
	v_mul_f32_e32 v190, 0xbfb8aa3b, v28
	v_fma_f32 v29, v29, s98, v190
	v_fma_f32 v30, v30, s98, v190
	v_fma_f32 v31, v31, s98, v190
	v_fma_f32 v32, v32, s98, v190
	v_fma_f32 v33, v33, s98, v190
	v_fma_f32 v34, v34, s98, v190
	v_fma_f32 v35, v35, s98, v190
	v_fma_f32 v36, v36, s98, v190
	v_exp_f32_e32 v29, v29
	v_exp_f32_e32 v30, v30
	v_exp_f32_e32 v31, v31
	v_exp_f32_e32 v32, v32
	v_exp_f32_e32 v33, v33
	v_exp_f32_e32 v34, v34
	v_exp_f32_e32 v35, v35
	v_exp_f32_e32 v36, v36
	v_add_u32_e32 v108, v77, v72
	v_add_u32_e32 v77, v77, v73
	ds_read_b64 v[124:125], v108 offset:24576
	ds_read_b64 v[126:127], v77 offset:24576
	ds_read_b64 v[128:129], v108 offset:26624
	ds_read_b64 v[130:131], v77 offset:26624
	s_waitcnt lgkmcnt(0)
	ds_read_b64 v[132:133], v106 offset:28672
	ds_read_b64 v[134:135], v107 offset:28672
	ds_read_b64 v[136:137], v106 offset:30720
	ds_read_b64 v[138:139], v107 offset:30720
	ds_read_b64 v[140:141], v108 offset:28672
	ds_read_b64 v[142:143], v77 offset:28672
	ds_read_b64 v[160:161], v108 offset:30720
	ds_read_b64 v[162:163], v77 offset:30720
	v_fma_f32 v37, v37, s98, v190
	v_fma_f32 v38, v38, s98, v190
	v_fma_f32 v39, v39, s98, v190
	v_fma_f32 v49, v49, s98, v190
	v_fma_f32 v51, v51, s98, v190
	v_fma_f32 v55, v55, s98, v190
	v_fma_f32 v60, v60, s98, v190
	v_fma_f32 v76, v76, s98, v190
	v_cndmask_b32_e64 v29, 0, v29, s[66:67]
	v_cndmask_b32_e64 v30, 0, v30, s[70:71]
	v_cndmask_b32_e64 v31, 0, v31, s[68:69]
	v_cndmask_b32_e64 v32, 0, v32, s[64:65]
	v_cndmask_b32_e64 v33, 0, v33, s[62:63]
	v_cndmask_b32_e64 v34, 0, v34, s[60:61]
	v_cndmask_b32_e64 v35, 0, v35, s[58:59]
	v_cndmask_b32_e64 v36, 0, v36, s[56:57]
	v_exp_f32_e32 v37, v37
	v_exp_f32_e32 v38, v38
	v_exp_f32_e32 v39, v39
	v_exp_f32_e32 v49, v49
	v_exp_f32_e32 v51, v51
	v_exp_f32_e32 v55, v55
	v_exp_f32_e32 v60, v60
	v_exp_f32_e32 v76, v76
	v_cvt_pk_bf16_f32 v78, v29, v30
	v_cvt_pk_bf16_f32 v79, v31, v32
	v_cvt_pk_bf16_f32 v80, v33, v34
	v_cvt_pk_bf16_f32 v81, v35, v36
	v_cndmask_b32_e64 v37, 0, v37, s[54:55]
	v_cndmask_b32_e64 v38, 0, v38, s[52:53]
	v_mfma_f32_16x16x32_bf16 v[20:23], v[116:119], v[78:81], v[20:23]
	v_mfma_f32_16x16x32_bf16 v[8:11], v[120:123], v[78:81], v[8:11]
	v_cndmask_b32_e64 v39, 0, v39, s[50:51]
	v_cndmask_b32_e64 v49, 0, v49, s[48:49]
	v_cndmask_b32_e64 v51, 0, v51, s[46:47]
	v_cndmask_b32_e64 v55, 0, v55, s[44:45]
	v_cndmask_b32_e64 v60, 0, v60, s[42:43]
	v_cndmask_b32_e64 v76, 0, v76, s[40:41]
	v_cvt_pk_bf16_f32 v82, v37, v38
	v_cvt_pk_bf16_f32 v83, v39, v49
	v_cvt_pk_bf16_f32 v84, v51, v55
	v_cvt_pk_bf16_f32 v85, v60, v76
	s_mov_b64 s[40:41], -1
	s_and_b64 vcc, exec, s[30:31]
	v_mfma_f32_16x16x32_bf16 v[8:11], v[128:131], v[82:85], v[8:11]
	v_mfma_f32_16x16x32_bf16 v[20:23], v[124:127], v[82:85], v[20:23]
	s_waitcnt lgkmcnt(0)
	v_mfma_f32_16x16x32_bf16 v[4:7], v[132:135], v[78:81], v[4:7]
	v_mfma_f32_16x16x32_bf16 v[0:3], v[136:139], v[78:81], v[0:3]
	v_mfma_f32_16x16x32_bf16 v[4:7], v[140:143], v[82:85], v[4:7]
	v_mfma_f32_16x16x32_bf16 v[0:3], v[160:163], v[82:85], v[0:3]
	s_cbranch_vccz .LBB0_117
	s_waitcnt vmcnt(0)
	s_mov_b64 s[40:41], 0

; #define LAS __attribute__((address_space(3)))
; DI unsigned pk2(float lo, float hi) { const f32x2 v = {lo, hi}; const hbf16x2 b = __builtin_convertvector(v, hbf16x2); return __builtin_bit_cast(unsigned, b); }
; #define MFMA16(a, b, c) __builtin_amdgcn_mfma_f32_16x16x32_bf16((a), (b), (c), 0, 0, 0)
; template <bool SWA>
; DI void attn_phase(const Ctx& a, LAS unsigned char* lds) {
;     ...
;                 const float m_new = fmaxf(m_run, cmax);
;                 const float alpha = __builtin_amdgcn_exp2f((m_run - m_new) * LOG2E);
;                 float p[16], psum = 0.f;
; #pragma unroll
;                 for (int e = 0; e < 16; ++e) { p[e] = ok[e] ? __builtin_amdgcn_exp2f((sv[e] - m_new) * LOG2E) : 0.f; psum += p[e]; }
;                 l_run = l_run * alpha + psum; m_run = m_new;
;                 u32x4 pw0, pw1; pw0.x = pk2(p[0], p[1]); pw0.y = pk2(p[2], p[3]); pw0.z = pk2(p[4], p[5]); pw0.w = pk2(p[6], p[7]);
;                 pw1.x = pk2(p[8], p[9]); pw1.y = pk2(p[10], p[11]); pw1.z = pk2(p[12], p[13]); pw1.w = pk2(p[14], p[15]);
;                 const bf16x8 pf0 = __builtin_bit_cast(bf16x8, pw0), pf1 = __builtin_bit_cast(bf16x8, pw1);
;                 if (__builtin_amdgcn_ballot_w64(alpha != 1.f) != 0ull) {
; #pragma unroll
;                     for (int dt = 0; dt < 4; ++dt) o[dt] = o[dt] * alpha;
;                 }
;                 const int kc = (fq >> 1), kb8 = (fq & 1) * 8;
; #pragma unroll
;                 for (int dt = 0; dt < 4; ++dt) {
;                     const int d = 16 * dt + fr, sw = (d >> 1) & 7; const int vb = AT_V + buf * 8192 + d * 128 + kb8;
;                     const s16x4 v0 = *(const LAS s16x4*)(lds + vb + ((kc ^ sw) << 4)), v1 = *(const LAS s16x4*)(lds + vb + (((kc + 2) ^ sw) << 4));
;                     const s16x4 v2 = *(const LAS s16x4*)(lds + vb + (((kc + 4) ^ sw) << 4)), v3 = *(const LAS s16x4*)(lds + vb + (((kc + 6) ^ sw) << 4));
;                     o[dt] = MFMA16(__builtin_shufflevector(v0, v1, 0, 1, 2, 3, 4, 5, 6, 7), pf0, o[dt]);
;                     o[dt] = MFMA16(__builtin_shufflevector(v2, v3, 0, 1, 2, 3, 4, 5, 6, 7), pf1, o[dt]);
;                 }
.LBB0_153:
	ds_read2st64_b64 v[92:95], v77 offset0:64 offset1:68
	s_mov_b32 s98, 0x3fb8aa3b
	v_mul_f32_e32 v190, 0xbfb8aa3b, v87
	v_fma_f32 v24, v24, s98, v190
	v_fma_f32 v25, v25, s98, v190
	v_fma_f32 v26, v26, s98, v190
	v_fma_f32 v27, v27, s98, v190
	v_fma_f32 v28, v28, s98, v190
	v_fma_f32 v29, v29, s98, v190
	v_fma_f32 v30, v30, s98, v190
	v_fma_f32 v31, v31, s98, v190
	v_exp_f32_e32 v24, v24
	v_exp_f32_e32 v25, v25
	v_exp_f32_e32 v26, v26
	v_exp_f32_e32 v27, v27
	v_exp_f32_e32 v28, v28
	v_exp_f32_e32 v29, v29
	v_exp_f32_e32 v30, v30
	v_exp_f32_e32 v31, v31
	s_waitcnt lgkmcnt(0)
	v_mov_b32_e32 v98, v92
	v_mov_b32_e32 v99, v93
	ds_read2st64_b64 v[100:103], v78 offset0:64 offset1:68
	ds_read2st64_b64 v[104:107], v79 offset0:64 offset1:68
	ds_read2st64_b64 v[108:111], v80 offset0:64 offset1:68
	v_cvt_pk_bf16_f32 v88, v24, v25
	v_cvt_pk_bf16_f32 v89, v26, v27
	v_cvt_pk_bf16_f32 v90, v28, v29
	v_cvt_pk_bf16_f32 v91, v30, v31
	v_fma_f32 v32, v32, s98, v190
	v_fma_f32 v33, v33, s98, v190
	s_waitcnt lgkmcnt(0)
	v_mfma_f32_16x16x32_bf16 v[8:11], v[98:101], v[88:91], v[8:11]
	v_mov_b32_e32 v100, v94
	v_mov_b32_e32 v101, v95
	v_fma_f32 v34, v34, s98, v190
	v_fma_f32 v35, v35, s98, v190
	v_fma_f32 v36, v36, s98, v190
	v_fma_f32 v37, v37, s98, v190
	v_fma_f32 v38, v38, s98, v190
	v_fma_f32 v39, v39, s98, v190
	v_exp_f32_e32 v32, v32
	v_exp_f32_e32 v33, v33
	v_exp_f32_e32 v34, v34
	v_exp_f32_e32 v35, v35
	v_exp_f32_e32 v36, v36
	v_exp_f32_e32 v37, v37
	v_exp_f32_e32 v38, v38
	v_exp_f32_e32 v39, v39
	v_mov_b32_e32 v112, v104
	v_mov_b32_e32 v113, v105
	v_mov_b32_e32 v114, v108
	v_mov_b32_e32 v115, v109
	v_mfma_f32_16x16x32_bf16 v[20:23], v[100:103], v[88:91], v[20:23]
	v_mov_b32_e32 v108, v106
	v_mov_b32_e32 v109, v107
	ds_read2st64_b64 v[92:95], v77 offset0:72 offset1:76
	ds_read2st64_b64 v[100:103], v78 offset0:72 offset1:76
	v_cvt_pk_bf16_f32 v96, v32, v33
	v_cvt_pk_bf16_f32 v97, v34, v35
	v_cvt_pk_bf16_f32 v98, v36, v37
	v_cvt_pk_bf16_f32 v99, v38, v39
	s_waitcnt lgkmcnt(0)
	v_mov_b32_e32 v104, v92
	v_mov_b32_e32 v105, v93
	v_mfma_f32_16x16x32_bf16 v[8:11], v[112:115], v[96:99], v[8:11]
	v_mov_b32_e32 v106, v100
	v_mov_b32_e32 v107, v101
	v_mov_b32_e32 v100, v94
	v_mfma_f32_16x16x32_bf16 v[20:23], v[108:111], v[96:99], v[20:23]
	ds_read2st64_b64 v[108:111], v79 offset0:72 offset1:76
	ds_read2st64_b64 v[112:115], v80 offset0:72 offset1:76
	v_mov_b32_e32 v101, v95
	s_andn2_b64 vcc, exec, s[30:31]
	v_mfma_f32_16x16x32_bf16 v[16:19], v[104:107], v[88:91], v[16:19]
	s_waitcnt lgkmcnt(0)
	v_mov_b32_e32 v104, v108
	v_mov_b32_e32 v105, v109
	v_mov_b32_e32 v106, v112
	v_mov_b32_e32 v107, v113
	v_mov_b32_e32 v112, v110
	v_mov_b32_e32 v113, v111
	v_mfma_f32_16x16x32_bf16 v[12:15], v[100:103], v[88:91], v[12:15]
	s_mov_b64 s[30:31], -1
	v_mfma_f32_16x16x32_bf16 v[16:19], v[104:107], v[96:99], v[16:19]
	v_mfma_f32_16x16x32_bf16 v[12:15], v[112:115], v[96:99], v[12:15]
	s_cbranch_vccnz .LBB0_155
	s_waitcnt vmcnt(0)
	s_mov_b64 s[30:31], 0

; #define LAS __attribute__((address_space(3)))
; DI unsigned pk2(float lo, float hi) { const f32x2 v = {lo, hi}; const hbf16x2 b = __builtin_convertvector(v, hbf16x2); return __builtin_bit_cast(unsigned, b); }
; #define MFMA16(a, b, c) __builtin_amdgcn_mfma_f32_16x16x32_bf16((a), (b), (c), 0, 0, 0)
; template <bool SWA>
; DI void attn_phase(const Ctx& a, LAS unsigned char* lds) {
;     ...
;                 const float m_new = fmaxf(m_run, cmax);
;                 const float alpha = __builtin_amdgcn_exp2f((m_run - m_new) * LOG2E);
;                 float p[16], psum = 0.f;
; #pragma unroll
;                 for (int e = 0; e < 16; ++e) { p[e] = ok[e] ? __builtin_amdgcn_exp2f((sv[e] - m_new) * LOG2E) : 0.f; psum += p[e]; }
;                 l_run = l_run * alpha + psum; m_run = m_new;
;                 u32x4 pw0, pw1; pw0.x = pk2(p[0], p[1]); pw0.y = pk2(p[2], p[3]); pw0.z = pk2(p[4], p[5]); pw0.w = pk2(p[6], p[7]);
;                 pw1.x = pk2(p[8], p[9]); pw1.y = pk2(p[10], p[11]); pw1.z = pk2(p[12], p[13]); pw1.w = pk2(p[14], p[15]);
;                 const bf16x8 pf0 = __builtin_bit_cast(bf16x8, pw0), pf1 = __builtin_bit_cast(bf16x8, pw1);
;                 if (__builtin_amdgcn_ballot_w64(alpha != 1.f) != 0ull) {
; #pragma unroll
;                     for (int dt = 0; dt < 4; ++dt) o[dt] = o[dt] * alpha;
;                 }
;                 const int kc = (fq >> 1), kb8 = (fq & 1) * 8;
; #pragma unroll
;                 for (int dt = 0; dt < 4; ++dt) {
;                     const int d = 16 * dt + fr, sw = (d >> 1) & 7; const int vb = AT_V + buf * 8192 + d * 128 + kb8;
;                     const s16x4 v0 = *(const LAS s16x4*)(lds + vb + ((kc ^ sw) << 4)), v1 = *(const LAS s16x4*)(lds + vb + (((kc + 2) ^ sw) << 4));
;                     const s16x4 v2 = *(const LAS s16x4*)(lds + vb + (((kc + 4) ^ sw) << 4)), v3 = *(const LAS s16x4*)(lds + vb + (((kc + 6) ^ sw) << 4));
;                     o[dt] = MFMA16(__builtin_shufflevector(v0, v1, 0, 1, 2, 3, 4, 5, 6, 7), pf0, o[dt]);
;                     o[dt] = MFMA16(__builtin_shufflevector(v2, v3, 0, 1, 2, 3, 4, 5, 6, 7), pf1, o[dt]);
;                 }
.LBB0_162:
	ds_read2st64_b64 v[92:95], v77 offset0:80 offset1:84
	s_mov_b32 s98, 0x3fb8aa3b
	v_mul_f32_e32 v190, 0xbfb8aa3b, v85
	v_fma_f32 v24, v24, s98, v190
	v_fma_f32 v25, v25, s98, v190
	v_fma_f32 v26, v26, s98, v190
	v_fma_f32 v27, v27, s98, v190
	v_fma_f32 v28, v28, s98, v190
	v_fma_f32 v29, v29, s98, v190
	v_fma_f32 v30, v30, s98, v190
	v_fma_f32 v31, v31, s98, v190
	v_exp_f32_e32 v24, v24
	v_exp_f32_e32 v25, v25
	v_exp_f32_e32 v26, v26
	v_exp_f32_e32 v27, v27
	v_exp_f32_e32 v28, v28
	v_exp_f32_e32 v29, v29
	v_exp_f32_e32 v30, v30
	v_exp_f32_e32 v31, v31
	s_waitcnt lgkmcnt(0)
	v_mov_b32_e32 v98, v92
	v_mov_b32_e32 v99, v93
	ds_read2st64_b64 v[100:103], v78 offset0:80 offset1:84
	ds_read2st64_b64 v[104:107], v79 offset0:80 offset1:84
	ds_read2st64_b64 v[108:111], v80 offset0:80 offset1:84
	v_cvt_pk_bf16_f32 v88, v24, v25
	v_cvt_pk_bf16_f32 v89, v26, v27
	v_cvt_pk_bf16_f32 v90, v28, v29
	v_cvt_pk_bf16_f32 v91, v30, v31
	v_fma_f32 v32, v32, s98, v190
	v_fma_f32 v33, v33, s98, v190
	s_waitcnt lgkmcnt(0)
	v_mfma_f32_16x16x32_bf16 v[8:11], v[98:101], v[88:91], v[8:11]
	v_mov_b32_e32 v100, v94
	v_mov_b32_e32 v101, v95
	v_fma_f32 v34, v34, s98, v190
	v_fma_f32 v35, v35, s98, v190
	v_fma_f32 v36, v36, s98, v190
	v_fma_f32 v37, v37, s98, v190
	v_fma_f32 v38, v38, s98, v190
	v_fma_f32 v39, v39, s98, v190
	v_exp_f32_e32 v32, v32
	v_exp_f32_e32 v33, v33
	v_exp_f32_e32 v34, v34
	v_exp_f32_e32 v35, v35
	v_exp_f32_e32 v36, v36
	v_exp_f32_e32 v37, v37
	v_exp_f32_e32 v38, v38
	v_exp_f32_e32 v39, v39
	v_mov_b32_e32 v112, v104
	v_mov_b32_e32 v113, v105
	v_mov_b32_e32 v114, v108
	v_mov_b32_e32 v115, v109
	v_mfma_f32_16x16x32_bf16 v[20:23], v[100:103], v[88:91], v[20:23]
	v_mov_b32_e32 v108, v106
	v_mov_b32_e32 v109, v107
	ds_read2st64_b64 v[92:95], v77 offset0:88 offset1:92
	ds_read2st64_b64 v[100:103], v78 offset0:88 offset1:92
	v_cvt_pk_bf16_f32 v96, v32, v33
	v_cvt_pk_bf16_f32 v97, v34, v35
	v_cvt_pk_bf16_f32 v98, v36, v37
	v_cvt_pk_bf16_f32 v99, v38, v39
	s_waitcnt lgkmcnt(0)
	v_mov_b32_e32 v104, v92
	v_mov_b32_e32 v105, v93
	v_mfma_f32_16x16x32_bf16 v[8:11], v[112:115], v[96:99], v[8:11]
	v_mov_b32_e32 v106, v100
	v_mov_b32_e32 v107, v101
	v_mov_b32_e32 v100, v94
	v_mfma_f32_16x16x32_bf16 v[20:23], v[108:111], v[96:99], v[20:23]
	ds_read2st64_b64 v[108:111], v79 offset0:88 offset1:92
	ds_read2st64_b64 v[112:115], v80 offset0:88 offset1:92
	v_mov_b32_e32 v101, v95
	s_andn2_b64 vcc, exec, s[30:31]
	v_mfma_f32_16x16x32_bf16 v[16:19], v[104:107], v[88:91], v[16:19]
	s_waitcnt lgkmcnt(0)
	v_mov_b32_e32 v104, v108
	v_mov_b32_e32 v105, v109
	v_mov_b32_e32 v106, v112
	v_mov_b32_e32 v107, v113
	v_mov_b32_e32 v112, v110
	v_mov_b32_e32 v113, v111
	v_mfma_f32_16x16x32_bf16 v[12:15], v[100:103], v[88:91], v[12:15]
	s_mov_b64 s[30:31], -1
	v_mfma_f32_16x16x32_bf16 v[16:19], v[104:107], v[96:99], v[16:19]
	v_mfma_f32_16x16x32_bf16 v[12:15], v[112:115], v[96:99], v[12:15]
	s_cbranch_vccnz .LBB0_164
	s_waitcnt vmcnt(0)
	s_mov_b64 s[30:31], 0

; #define LAS __attribute__((address_space(3)))
; DI unsigned pk2(float lo, float hi) { const f32x2 v = {lo, hi}; const hbf16x2 b = __builtin_convertvector(v, hbf16x2); return __builtin_bit_cast(unsigned, b); }
; #define MFMA16(a, b, c) __builtin_amdgcn_mfma_f32_16x16x32_bf16((a), (b), (c), 0, 0, 0)
; template <bool SWA>
; DI void attn_phase(const Ctx& a, LAS unsigned char* lds) {
;     ...
;                 const float m_new = fmaxf(m_run, cmax);
;                 const float alpha = __builtin_amdgcn_exp2f((m_run - m_new) * LOG2E);
;                 float p[16], psum = 0.f;
; #pragma unroll
;                 for (int e = 0; e < 16; ++e) { p[e] = ok[e] ? __builtin_amdgcn_exp2f((sv[e] - m_new) * LOG2E) : 0.f; psum += p[e]; }
;                 l_run = l_run * alpha + psum; m_run = m_new;
;                 u32x4 pw0, pw1; pw0.x = pk2(p[0], p[1]); pw0.y = pk2(p[2], p[3]); pw0.z = pk2(p[4], p[5]); pw0.w = pk2(p[6], p[7]);
;                 pw1.x = pk2(p[8], p[9]); pw1.y = pk2(p[10], p[11]); pw1.z = pk2(p[12], p[13]); pw1.w = pk2(p[14], p[15]);
;                 const bf16x8 pf0 = __builtin_bit_cast(bf16x8, pw0), pf1 = __builtin_bit_cast(bf16x8, pw1);
;                 if (__builtin_amdgcn_ballot_w64(alpha != 1.f) != 0ull) {
; #pragma unroll
;                     for (int dt = 0; dt < 4; ++dt) o[dt] = o[dt] * alpha;
;                 }
;                 const int kc = (fq >> 1), kb8 = (fq & 1) * 8;
; #pragma unroll
;                 for (int dt = 0; dt < 4; ++dt) {
;                     const int d = 16 * dt + fr, sw = (d >> 1) & 7; const int vb = AT_V + buf * 8192 + d * 128 + kb8;
;                     const s16x4 v0 = *(const LAS s16x4*)(lds + vb + ((kc ^ sw) << 4)), v1 = *(const LAS s16x4*)(lds + vb + (((kc + 2) ^ sw) << 4));
;                     const s16x4 v2 = *(const LAS s16x4*)(lds + vb + (((kc + 4) ^ sw) << 4)), v3 = *(const LAS s16x4*)(lds + vb + (((kc + 6) ^ sw) << 4));
;                     o[dt] = MFMA16(__builtin_shufflevector(v0, v1, 0, 1, 2, 3, 4, 5, 6, 7), pf0, o[dt]);
;                     o[dt] = MFMA16(__builtin_shufflevector(v2, v3, 0, 1, 2, 3, 4, 5, 6, 7), pf1, o[dt]);
;                 }
.LBB0_171:
	ds_read2st64_b64 v[90:93], v77 offset0:48 offset1:52
	s_mov_b32 s98, 0x3fb8aa3b
	v_mul_f32_e32 v190, 0xbfb8aa3b, v49
	v_fma_f32 v24, v24, s98, v190
	v_fma_f32 v25, v25, s98, v190
	v_fma_f32 v26, v26, s98, v190
	v_fma_f32 v27, v27, s98, v190
	v_fma_f32 v28, v28, s98, v190
	v_fma_f32 v29, v29, s98, v190
	v_fma_f32 v30, v30, s98, v190
	v_fma_f32 v31, v31, s98, v190
	v_exp_f32_e32 v24, v24
	v_exp_f32_e32 v25, v25
	v_exp_f32_e32 v26, v26
	v_exp_f32_e32 v27, v27
	v_exp_f32_e32 v28, v28
	v_exp_f32_e32 v29, v29
	v_exp_f32_e32 v30, v30
	v_exp_f32_e32 v31, v31
	s_waitcnt lgkmcnt(0)
	v_mov_b32_e32 v96, v90
	v_mov_b32_e32 v97, v91
	ds_read2st64_b64 v[98:101], v78 offset0:48 offset1:52
	ds_read2st64_b64 v[102:105], v79 offset0:48 offset1:52
	ds_read2st64_b64 v[106:109], v80 offset0:48 offset1:52
	v_cvt_pk_bf16_f32 v86, v24, v25
	v_cvt_pk_bf16_f32 v87, v26, v27
	v_cvt_pk_bf16_f32 v88, v28, v29
	v_cvt_pk_bf16_f32 v89, v30, v31
	v_fma_f32 v32, v32, s98, v190
	v_fma_f32 v33, v33, s98, v190
	s_waitcnt lgkmcnt(0)
	v_mfma_f32_16x16x32_bf16 v[8:11], v[96:99], v[86:89], v[8:11]
	v_mov_b32_e32 v98, v92
	v_mov_b32_e32 v99, v93
	v_fma_f32 v34, v34, s98, v190
	v_fma_f32 v35, v35, s98, v190
	v_fma_f32 v36, v36, s98, v190
	v_fma_f32 v37, v37, s98, v190
	v_fma_f32 v38, v38, s98, v190
	v_fma_f32 v39, v39, s98, v190
	v_exp_f32_e32 v32, v32
	v_exp_f32_e32 v33, v33
	v_exp_f32_e32 v34, v34
	v_exp_f32_e32 v35, v35
	v_exp_f32_e32 v36, v36
	v_exp_f32_e32 v37, v37
	v_exp_f32_e32 v38, v38
	v_exp_f32_e32 v39, v39
	v_mov_b32_e32 v110, v102
	v_mov_b32_e32 v111, v103
	v_mov_b32_e32 v112, v106
	v_mov_b32_e32 v113, v107
	v_mfma_f32_16x16x32_bf16 v[20:23], v[98:101], v[86:89], v[20:23]
	v_mov_b32_e32 v106, v104
	v_mov_b32_e32 v107, v105
	ds_read2st64_b64 v[90:93], v77 offset0:56 offset1:60
	ds_read2st64_b64 v[98:101], v78 offset0:56 offset1:60
	v_cvt_pk_bf16_f32 v94, v32, v33
	v_cvt_pk_bf16_f32 v95, v34, v35
	v_cvt_pk_bf16_f32 v96, v36, v37
	v_cvt_pk_bf16_f32 v97, v38, v39
	s_waitcnt lgkmcnt(0)
	v_mov_b32_e32 v102, v90
	v_mov_b32_e32 v103, v91
	v_mfma_f32_16x16x32_bf16 v[8:11], v[110:113], v[94:97], v[8:11]
	v_mov_b32_e32 v104, v98
	v_mov_b32_e32 v105, v99
	v_mov_b32_e32 v98, v92
	v_mfma_f32_16x16x32_bf16 v[20:23], v[106:109], v[94:97], v[20:23]
	ds_read2st64_b64 v[106:109], v79 offset0:56 offset1:60
	ds_read2st64_b64 v[110:113], v80 offset0:56 offset1:60
	v_mov_b32_e32 v99, v93
	s_andn2_b64 vcc, exec, s[30:31]
	v_mfma_f32_16x16x32_bf16 v[16:19], v[102:105], v[86:89], v[16:19]
	s_waitcnt lgkmcnt(0)
	v_mov_b32_e32 v102, v106
	v_mov_b32_e32 v103, v107
	v_mov_b32_e32 v104, v110
	v_mov_b32_e32 v105, v111
	v_mov_b32_e32 v110, v108
	v_mov_b32_e32 v111, v109
	v_mfma_f32_16x16x32_bf16 v[12:15], v[98:101], v[86:89], v[12:15]
	s_mov_b64 s[30:31], -1
	v_mfma_f32_16x16x32_bf16 v[16:19], v[102:105], v[94:97], v[16:19]
	v_mfma_f32_16x16x32_bf16 v[12:15], v[110:113], v[94:97], v[12:15]
	s_cbranch_vccnz .LBB0_173
	s_waitcnt vmcnt(0)
	s_mov_b64 s[30:31], 0
